# static s_setprio 1 for waves 0-3 (leading half) before each GEMM K-loop, per-MFMA-block priority flips deleted
# speedup vs baseline: 1.0008x; 1.0008x over previous
.LBB0_164:
	s_lshl_b32 s26, s8, 6
	v_ashrrev_i32_e32 v14, 6, v144
	s_lshl_b32 s8, s8, 13
	v_lshl_add_u32 v16, v14, 10, s8
	s_lshl_b32 s8, s88, 5
	s_and_b32 s20, s8, 0x60
	s_lshr_b32 s8, s20, 3
	v_add_lshl_u32 v14, v14, s8, 10
	s_mov_b64 s[8:9], 0x80
	s_add_i32 m0, s23, 0x18000
	v_lshl_add_u64 v[6:7], v[6:7], 0, s[8:9]
	s_waitcnt vmcnt(2)
	s_barrier
	global_load_lds_dwordx4 v[6:7], off
	v_lshl_add_u64 v[4:5], v[4:5], 0, s[8:9]
	s_add_i32 m0, s23, 0x1a000
	s_add_i32 s30, s23, 0x8000
	s_add_i32 s31, s23, 0xa000
	global_load_lds_dwordx4 v[4:5], off
	v_lshl_add_u64 v[2:3], v[2:3], 0, s[8:9]
	s_mov_b32 m0, s30
	s_add_u32 s16, s2, 0x80080
	global_load_lds_dwordx4 v[2:3], off
	v_lshl_add_u64 v[0:1], v[0:1], 0, s[8:9]
	s_mov_b32 m0, s31
	s_addc_u32 s17, s3, 0
	global_load_lds_dwordx4 v[0:1], off
	s_add_i32 m0, s23, 0x1c000
	v_lshl_add_u64 v[0:1], s[16:17], 0, v[130:131]
	global_load_lds_dwordx4 v[0:1], off
	v_lshl_add_u64 v[0:1], s[16:17], 0, v[134:135]
	s_add_i32 m0, s23, 0x1e000
	s_add_u32 s10, s94, s10
	global_load_lds_dwordx4 v[0:1], off
	v_lshlrev_b32_e32 v0, 15, v8
	v_and_b32_e32 v0, 0xffff0000, v0
	v_lshl_add_u32 v0, v9, 12, v0
	v_and_b32_e32 v1, 1, v8
	v_lshl_or_b32 v0, v1, 6, v0
	s_addc_u32 s11, s95, 0
	v_lshl_add_u32 v0, v10, 1, v0
	v_mov_b32_e32 v1, v131
	v_lshl_add_u64 v[0:1], s[10:11], 0, v[0:1]
	s_mov_b64 s[16:17], 0x11280080
	v_lshl_add_u64 v[136:137], v[0:1], 0, s[16:17]
	v_lshlrev_b32_e32 v0, 15, v11
	v_and_b32_e32 v0, 0xffff0000, v0
	v_lshl_add_u32 v0, v12, 12, v0
	v_and_b32_e32 v1, 1, v11
	v_lshl_or_b32 v0, v1, 6, v0
	v_lshl_add_u32 v0, v13, 1, v0
	v_mov_b32_e32 v1, v131
	v_lshl_add_u64 v[0:1], s[10:11], 0, v[0:1]
	v_lshl_add_u64 v[138:139], v[0:1], 0, s[16:17]
	s_lshl_b32 s15, s49, 18
	s_lshl_b32 s16, s62, 16
	s_and_b32 s15, s15, 0xe00000
	s_and_b32 s16, s16, 0x100000
	s_or_b32 s15, s15, s16
	s_add_u32 s12, s12, s15
	s_addc_u32 s13, s13, 0
	s_add_u32 s12, s94, s12
	v_and_b32_e32 v140, 15, v144
	v_and_b32_e32 v15, 48, v144
	v_lshlrev_b32_e32 v17, 2, v144
	s_addc_u32 s13, s95, s13
	v_lshl_or_b32 v15, v140, 6, v15
	v_and_b32_e32 v17, 32, v17
	s_add_u32 s34, s12, 0x4200100
	v_bitop3_b32 v14, v15, v14, v17 bitop3:0xde
	s_waitcnt vmcnt(6)
	s_addc_u32 s35, s13, 0
	s_add_i32 s39, 0, 0x10000
	s_add_i32 s41, 0, 0x14000
	s_add_i32 s43, 0, 0x18000
	s_add_i32 s45, 0, 0x1c000
	v_bitop3_b32 v16, v15, v16, v17 bitop3:0xde
	v_add_u32_e32 v141, s39, v14
	v_add_u32_e32 v142, s41, v14
	s_add_i32 s39, s39, s14
	s_add_i32 s41, s41, s14
	v_add_u32_e32 v145, s43, v14
	v_add_u32_e32 v146, s45, v14
	s_add_i32 s43, s43, s14
	s_add_i32 s45, s45, s14
	s_mov_b32 s36, -2
	s_mov_b64 s[12:13], 0
	v_add_u32_e32 v143, 0, v16
	s_add_i32 s37, s23, 0xc000
	s_add_i32 s38, s23, 0xe000
	s_add_i32 s40, s39, 0x2000
	s_add_i32 s42, s41, 0x2000
	s_add_i32 s44, s43, 0x2000
	s_add_i32 s46, s45, 0x2000
	v_mov_b32_e32 v0, v131
	v_mov_b32_e32 v1, v131
	v_mov_b32_e32 v2, v131
	v_mov_b32_e32 v3, v131
	v_mov_b32_e32 v4, v131
	v_mov_b32_e32 v5, v131
	v_mov_b32_e32 v6, v131
	v_mov_b32_e32 v7, v131
	v_mov_b32_e32 v16, v131
	v_mov_b32_e32 v17, v131
	v_mov_b32_e32 v18, v131
	v_mov_b32_e32 v19, v131
	v_mov_b32_e32 v20, v131
	v_mov_b32_e32 v21, v131
	v_mov_b32_e32 v22, v131
	v_mov_b32_e32 v23, v131
	v_mov_b32_e32 v32, v131
	v_mov_b32_e32 v33, v131
	v_mov_b32_e32 v34, v131
	v_mov_b32_e32 v35, v131
	v_mov_b32_e32 v36, v131
	v_mov_b32_e32 v37, v131
	v_mov_b32_e32 v38, v131
	v_mov_b32_e32 v39, v131
	v_mov_b32_e32 v48, v131
	v_mov_b32_e32 v49, v131
	v_mov_b32_e32 v50, v131
	v_mov_b32_e32 v51, v131
	v_mov_b32_e32 v52, v131
	v_mov_b32_e32 v53, v131
	v_mov_b32_e32 v54, v131
	v_mov_b32_e32 v55, v131
	v_mov_b32_e32 v8, v131
	v_mov_b32_e32 v9, v131
	v_mov_b32_e32 v10, v131
	v_mov_b32_e32 v11, v131
	v_mov_b32_e32 v12, v131
	v_mov_b32_e32 v13, v131
	v_mov_b32_e32 v14, v131
	v_mov_b32_e32 v15, v131
	v_mov_b32_e32 v24, v131
	v_mov_b32_e32 v25, v131
	v_mov_b32_e32 v26, v131
	v_mov_b32_e32 v27, v131
	v_mov_b32_e32 v28, v131
	v_mov_b32_e32 v29, v131
	v_mov_b32_e32 v30, v131
	v_mov_b32_e32 v31, v131
	v_mov_b32_e32 v40, v131
	v_mov_b32_e32 v41, v131
	v_mov_b32_e32 v42, v131
	v_mov_b32_e32 v43, v131
	v_mov_b32_e32 v44, v131
	v_mov_b32_e32 v45, v131
	v_mov_b32_e32 v46, v131
	v_mov_b32_e32 v47, v131
	v_mov_b32_e32 v56, v131
	v_mov_b32_e32 v57, v131
	v_mov_b32_e32 v58, v131
	v_mov_b32_e32 v59, v131
	v_mov_b32_e32 v60, v131
	v_mov_b32_e32 v61, v131
	v_mov_b32_e32 v62, v131
	v_mov_b32_e32 v63, v131
	v_mov_b32_e32 v64, v131
	v_mov_b32_e32 v65, v131
	v_mov_b32_e32 v66, v131
	v_mov_b32_e32 v67, v131
	v_mov_b32_e32 v68, v131
	v_mov_b32_e32 v69, v131
	v_mov_b32_e32 v70, v131
	v_mov_b32_e32 v71, v131
	v_mov_b32_e32 v80, v131
	v_mov_b32_e32 v81, v131
	v_mov_b32_e32 v82, v131
	v_mov_b32_e32 v83, v131
	v_mov_b32_e32 v84, v131
	v_mov_b32_e32 v85, v131
	v_mov_b32_e32 v86, v131
	v_mov_b32_e32 v87, v131
	v_mov_b32_e32 v96, v131
	v_mov_b32_e32 v97, v131
	v_mov_b32_e32 v98, v131
	v_mov_b32_e32 v99, v131
	v_mov_b32_e32 v100, v131
	v_mov_b32_e32 v101, v131
	v_mov_b32_e32 v102, v131
	v_mov_b32_e32 v103, v131
	v_mov_b32_e32 v112, v131
	v_mov_b32_e32 v113, v131
	v_mov_b32_e32 v114, v131
	v_mov_b32_e32 v115, v131
	v_mov_b32_e32 v116, v131
	v_mov_b32_e32 v117, v131
	v_mov_b32_e32 v118, v131
	v_mov_b32_e32 v119, v131
	v_mov_b32_e32 v72, v131
	v_mov_b32_e32 v73, v131
	v_mov_b32_e32 v74, v131
	v_mov_b32_e32 v75, v131
	v_mov_b32_e32 v76, v131
	v_mov_b32_e32 v77, v131
	v_mov_b32_e32 v78, v131
	v_mov_b32_e32 v79, v131
	v_mov_b32_e32 v88, v131
	v_mov_b32_e32 v89, v131
	v_mov_b32_e32 v90, v131
	v_mov_b32_e32 v91, v131
	v_mov_b32_e32 v92, v131
	v_mov_b32_e32 v93, v131
	v_mov_b32_e32 v94, v131
	v_mov_b32_e32 v95, v131
	v_mov_b32_e32 v104, v131
	v_mov_b32_e32 v105, v131
	v_mov_b32_e32 v106, v131
	v_mov_b32_e32 v107, v131
	v_mov_b32_e32 v108, v131
	v_mov_b32_e32 v109, v131
	v_mov_b32_e32 v110, v131
	v_mov_b32_e32 v111, v131
	v_mov_b32_e32 v120, v131
	v_mov_b32_e32 v121, v131
	v_mov_b32_e32 v122, v131
	v_mov_b32_e32 v123, v131
	v_mov_b32_e32 v124, v131
	v_mov_b32_e32 v125, v131
	v_mov_b32_e32 v126, v131
	v_mov_b32_e32 v127, v131
	s_barrier
	s_lshr_b32 s101, s88, 2
	s_cmp_lg_u32 s101, 0
	s_cbranch_scc1 .Lprio_skip0
	s_setprio 1

.LBB0_253:
	s_add_i32 s54, s54, 1
	s_mov_b64 s[2:3], s[10:11]
	s_mov_b32 s60, s6
	s_mov_b32 s10, s6
	s_lshl_b32 s6, s54, 5
	s_add_i32 s6, s6, s63
	s_cmp_lt_i32 s6, 64
	s_cselect_b64 s[44:45], -1, 0
	s_ashr_i32 s6, s6, 2
	s_mov_b64 s[0:1], s[8:9]
	s_and_b64 s[8:9], s[44:45], exec
	s_cselect_b32 s8, s35, s35
	s_cselect_b32 s10, s6, s10
	s_ashr_i32 s9, s8, 31
	s_lshl_b64 s[8:9], s[8:9], 20
	s_add_u32 s8, s21, s8
	s_addc_u32 s9, s23, s9
	s_and_b64 s[46:47], s[44:45], exec
	s_cselect_b32 s61, s9, s1
	s_cselect_b32 s72, s8, s0
	s_ashr_i32 s11, s10, 31
	s_lshl_b64 s[10:11], s[10:11], 20
	s_add_u32 s10, s70, s10
	s_addc_u32 s11, s71, s11
	s_and_b64 s[46:47], s[44:45], exec
	s_cselect_b32 s73, s11, s3
	s_cselect_b32 s74, s10, s2
	s_add_u32 s0, s0, 0x80080
	s_addc_u32 s1, s1, 0
	s_add_u32 s75, s2, 0x100
	s_addc_u32 s76, s3, 0
	s_mov_b32 s77, -2
	v_mov_b32_e32 v0, 0
	v_mov_b32_e32 v1, v158
	s_waitcnt lgkmcnt(0)
	v_mov_b32_e32 v2, v158
	v_mov_b32_e32 v3, v158
	v_mov_b32_e32 v4, 0
	v_mov_b32_e32 v5, v158
	v_mov_b32_e32 v6, v158
	v_mov_b32_e32 v7, v158
	v_mov_b32_e32 v16, 0
	v_mov_b32_e32 v17, v158
	v_mov_b32_e32 v18, v158
	v_mov_b32_e32 v19, v158
	v_mov_b32_e32 v20, 0
	v_mov_b32_e32 v21, v158
	v_mov_b32_e32 v22, v158
	v_mov_b32_e32 v23, v158
	v_mov_b32_e32 v32, 0
	v_mov_b32_e32 v33, v158
	v_mov_b32_e32 v34, v158
	v_mov_b32_e32 v35, v158
	v_mov_b32_e32 v36, 0
	v_mov_b32_e32 v37, v158
	v_mov_b32_e32 v38, v158
	v_mov_b32_e32 v39, v158
	v_mov_b32_e32 v64, 0
	v_mov_b32_e32 v65, v158
	v_mov_b32_e32 v66, v158
	v_mov_b32_e32 v67, v158
	v_mov_b32_e32 v68, 0
	v_mov_b32_e32 v69, v158
	v_mov_b32_e32 v70, v158
	v_mov_b32_e32 v71, v158
	v_mov_b32_e32 v8, 0
	v_mov_b32_e32 v9, v158
	v_mov_b32_e32 v10, v158
	v_mov_b32_e32 v11, v158
	v_mov_b32_e32 v12, 0
	v_mov_b32_e32 v13, v158
	v_mov_b32_e32 v14, v158
	v_mov_b32_e32 v15, v158
	v_mov_b32_e32 v24, 0
	v_mov_b32_e32 v25, v158
	v_mov_b32_e32 v26, v158
	v_mov_b32_e32 v27, v158
	v_mov_b32_e32 v28, 0
	v_mov_b32_e32 v29, v158
	v_mov_b32_e32 v30, v158
	v_mov_b32_e32 v31, v158
	v_mov_b32_e32 v56, 0
	v_mov_b32_e32 v57, v158
	v_mov_b32_e32 v58, v158
	v_mov_b32_e32 v59, v158
	v_mov_b32_e32 v60, 0
	v_mov_b32_e32 v61, v158
	v_mov_b32_e32 v62, v158
	v_mov_b32_e32 v63, v158
	v_mov_b32_e32 v72, 0
	v_mov_b32_e32 v73, v158
	v_mov_b32_e32 v74, v158
	v_mov_b32_e32 v75, v158
	v_mov_b32_e32 v76, 0
	v_mov_b32_e32 v77, v158
	v_mov_b32_e32 v78, v158
	v_mov_b32_e32 v79, v158
	v_mov_b32_e32 v80, 0
	v_mov_b32_e32 v81, v158
	v_mov_b32_e32 v82, v158
	v_mov_b32_e32 v83, v158
	v_mov_b32_e32 v84, 0
	v_mov_b32_e32 v85, v158
	v_mov_b32_e32 v86, v158
	v_mov_b32_e32 v87, v158
	v_mov_b32_e32 v96, 0
	v_mov_b32_e32 v97, v158
	v_mov_b32_e32 v98, v158
	v_mov_b32_e32 v99, v158
	v_mov_b32_e32 v100, 0
	v_mov_b32_e32 v101, v158
	v_mov_b32_e32 v102, v158
	v_mov_b32_e32 v103, v158
	v_mov_b32_e32 v112, 0
	v_mov_b32_e32 v113, v158
	v_mov_b32_e32 v114, v158
	v_mov_b32_e32 v115, v158
	v_mov_b32_e32 v116, 0
	v_mov_b32_e32 v117, v158
	v_mov_b32_e32 v118, v158
	v_mov_b32_e32 v119, v158
	v_mov_b32_e32 v128, 0
	v_mov_b32_e32 v129, v158
	v_mov_b32_e32 v130, v158
	v_mov_b32_e32 v131, v158
	v_mov_b32_e32 v132, 0
	v_mov_b32_e32 v133, v158
	v_mov_b32_e32 v134, v158
	v_mov_b32_e32 v135, v158
	v_mov_b32_e32 v88, 0
	v_mov_b32_e32 v89, v158
	v_mov_b32_e32 v90, v158
	v_mov_b32_e32 v91, v158
	v_mov_b32_e32 v92, 0
	v_mov_b32_e32 v93, v158
	v_mov_b32_e32 v94, v158
	v_mov_b32_e32 v95, v158
	v_mov_b32_e32 v104, 0
	v_mov_b32_e32 v105, v158
	v_mov_b32_e32 v106, v158
	v_mov_b32_e32 v107, v158
	v_mov_b32_e32 v108, 0
	v_mov_b32_e32 v109, v158
	v_mov_b32_e32 v110, v158
	v_mov_b32_e32 v111, v158
	v_mov_b32_e32 v120, 0
	v_mov_b32_e32 v121, v158
	v_mov_b32_e32 v122, v158
	v_mov_b32_e32 v123, v158
	v_mov_b32_e32 v124, 0
	v_mov_b32_e32 v125, v158
	v_mov_b32_e32 v126, v158
	v_mov_b32_e32 v127, v158
	v_mov_b32_e32 v136, 0
	v_mov_b32_e32 v137, v158
	v_mov_b32_e32 v138, v158
	v_mov_b32_e32 v139, v158
	v_mov_b32_e32 v140, 0
	v_mov_b32_e32 v141, v158
	v_mov_b32_e32 v142, v158
	v_mov_b32_e32 v143, v158
	s_lshr_b32 s101, s88, 2
	s_cmp_lg_u32 s101, 0
	s_cbranch_scc1 .Lprio_skip1
	s_setprio 1

.LBB0_294:
	s_or_b64 exec, exec, s[6:7]
	v_lshlrev_b32_e32 v0, 15, v186
	s_lshl_b32 s6, s64, 22
	s_lshl_b32 s7, s75, 20
	v_and_b32_e32 v0, 0xffff0000, v0
	s_or_b32 s6, s6, s7
	v_lshl_add_u32 v0, v187, 12, v0
	v_and_b32_e32 v1, 1, v186
	s_add_u32 s6, s94, s6
	v_lshl_or_b32 v0, v1, 6, v0
	s_addc_u32 s7, s95, 0
	v_lshl_add_u32 v0, v188, 1, v0
	v_mov_b32_e32 v1, 0
	v_lshl_add_u64 v[2:3], s[6:7], 0, v[0:1]
	v_lshlrev_b32_e32 v0, 15, v189
	s_mov_b64 s[10:11], 0xf280080
	v_and_b32_e32 v0, 0xffff0000, v0
	s_add_u32 s8, s94, s8
	v_lshl_add_u64 v[40:41], v[2:3], 0, s[10:11]
	v_lshl_add_u32 v0, v190, 12, v0
	v_and_b32_e32 v2, 1, v189
	s_addc_u32 s9, s95, 0
	v_lshl_or_b32 v0, v2, 6, v0
	s_add_u32 s21, s8, 0x200100
	v_lshl_add_u32 v0, v191, 1, v0
	s_addc_u32 s22, s9, 0
	s_add_i32 s44, 0, 0x10000
	s_add_i32 s46, 0, 0x14000
	s_add_i32 s49, 0, 0x18000
	s_add_i32 s51, 0, 0x1c000
	v_lshl_add_u64 v[2:3], s[6:7], 0, v[0:1]
	v_add_u32_e32 v44, s44, v192
	v_add_u32_e32 v45, s46, v192
	s_add_i32 s44, s44, s66
	s_add_i32 s46, s46, s66
	v_add_u32_e32 v47, s49, v192
	v_add_u32_e32 v48, s51, v192
	s_add_i32 s49, s49, s66
	s_add_i32 s51, s51, s66
	v_lshl_add_u64 v[42:43], v[2:3], 0, s[10:11]
	s_mov_b32 s23, -2
	s_mov_b64 s[8:9], 0
	v_add_u32_e32 v46, 0, v193
	s_add_i32 s42, s14, 0xc000
	s_add_i32 s43, s14, 0xe000
	s_add_i32 s45, s44, 0x2000
	s_add_i32 s47, s46, 0x2000
	s_add_i32 s50, s49, 0x2000
	s_add_i32 s52, s51, 0x2000
	v_mov_b32_e32 v0, v1
	v_mov_b32_e32 v2, v1
	v_mov_b32_e32 v3, v1
	v_mov_b32_e32 v4, v1
	v_mov_b32_e32 v5, v1
	v_mov_b32_e32 v6, v1
	v_mov_b32_e32 v7, v1
	v_mov_b32_e32 v16, v1
	v_mov_b32_e32 v17, v1
	v_mov_b32_e32 v18, v1
	v_mov_b32_e32 v19, v1
	v_mov_b32_e32 v20, v1
	v_mov_b32_e32 v21, v1
	v_mov_b32_e32 v22, v1
	v_mov_b32_e32 v23, v1
	v_mov_b32_e32 v32, v1
	v_mov_b32_e32 v33, v1
	v_mov_b32_e32 v34, v1
	v_mov_b32_e32 v35, v1
	v_mov_b32_e32 v36, v1
	v_mov_b32_e32 v37, v1
	v_mov_b32_e32 v38, v1
	v_mov_b32_e32 v39, v1
	v_mov_b32_e32 v64, v1
	v_mov_b32_e32 v65, v1
	v_mov_b32_e32 v66, v1
	v_mov_b32_e32 v67, v1
	v_mov_b32_e32 v68, v1
	v_mov_b32_e32 v69, v1
	v_mov_b32_e32 v70, v1
	v_mov_b32_e32 v71, v1
	v_mov_b32_e32 v8, v1
	v_mov_b32_e32 v9, v1
	v_mov_b32_e32 v10, v1
	v_mov_b32_e32 v11, v1
	v_mov_b32_e32 v12, v1
	v_mov_b32_e32 v13, v1
	v_mov_b32_e32 v14, v1
	v_mov_b32_e32 v15, v1
	v_mov_b32_e32 v24, v1
	v_mov_b32_e32 v25, v1
	v_mov_b32_e32 v26, v1
	v_mov_b32_e32 v27, v1
	v_mov_b32_e32 v28, v1
	v_mov_b32_e32 v29, v1
	v_mov_b32_e32 v30, v1
	v_mov_b32_e32 v31, v1
	v_mov_b32_e32 v56, v1
	v_mov_b32_e32 v57, v1
	v_mov_b32_e32 v58, v1
	v_mov_b32_e32 v59, v1
	v_mov_b32_e32 v60, v1
	v_mov_b32_e32 v61, v1
	v_mov_b32_e32 v62, v1
	v_mov_b32_e32 v63, v1
	v_mov_b32_e32 v72, v1
	v_mov_b32_e32 v73, v1
	v_mov_b32_e32 v74, v1
	v_mov_b32_e32 v75, v1
	v_mov_b32_e32 v76, v1
	v_mov_b32_e32 v77, v1
	v_mov_b32_e32 v78, v1
	v_mov_b32_e32 v79, v1
	v_mov_b32_e32 v80, v1
	v_mov_b32_e32 v81, v1
	v_mov_b32_e32 v82, v1
	v_mov_b32_e32 v83, v1
	v_mov_b32_e32 v84, v1
	v_mov_b32_e32 v85, v1
	v_mov_b32_e32 v86, v1
	v_mov_b32_e32 v87, v1
	v_mov_b32_e32 v96, v1
	v_mov_b32_e32 v97, v1
	v_mov_b32_e32 v98, v1
	v_mov_b32_e32 v99, v1
	v_mov_b32_e32 v100, v1
	v_mov_b32_e32 v101, v1
	v_mov_b32_e32 v102, v1
	v_mov_b32_e32 v103, v1
	v_mov_b32_e32 v112, v1
	v_mov_b32_e32 v113, v1
	v_mov_b32_e32 v114, v1
	v_mov_b32_e32 v115, v1
	v_mov_b32_e32 v116, v1
	v_mov_b32_e32 v117, v1
	v_mov_b32_e32 v118, v1
	v_mov_b32_e32 v119, v1
	v_mov_b32_e32 v128, v1
	v_mov_b32_e32 v129, v1
	v_mov_b32_e32 v130, v1
	v_mov_b32_e32 v131, v1
	v_mov_b32_e32 v132, v1
	v_mov_b32_e32 v133, v1
	v_mov_b32_e32 v134, v1
	v_mov_b32_e32 v135, v1
	v_mov_b32_e32 v88, v1
	v_mov_b32_e32 v89, v1
	v_mov_b32_e32 v90, v1
	v_mov_b32_e32 v91, v1
	v_mov_b32_e32 v92, v1
	v_mov_b32_e32 v93, v1
	v_mov_b32_e32 v94, v1
	v_mov_b32_e32 v95, v1
	v_mov_b32_e32 v104, v1
	v_mov_b32_e32 v105, v1
	v_mov_b32_e32 v106, v1
	v_mov_b32_e32 v107, v1
	v_mov_b32_e32 v108, v1
	v_mov_b32_e32 v109, v1
	v_mov_b32_e32 v110, v1
	v_mov_b32_e32 v111, v1
	v_mov_b32_e32 v120, v1
	v_mov_b32_e32 v121, v1
	v_mov_b32_e32 v122, v1
	v_mov_b32_e32 v123, v1
	v_mov_b32_e32 v124, v1
	v_mov_b32_e32 v125, v1
	v_mov_b32_e32 v126, v1
	v_mov_b32_e32 v127, v1
	v_mov_b32_e32 v136, v1
	v_mov_b32_e32 v137, v1
	v_mov_b32_e32 v138, v1
	v_mov_b32_e32 v139, v1
	v_mov_b32_e32 v140, v1
	v_mov_b32_e32 v141, v1
	v_mov_b32_e32 v142, v1
	v_mov_b32_e32 v143, v1
	s_lshr_b32 s101, s88, 2
	s_cmp_lg_u32 s101, 0
	s_cbranch_scc1 .Lprio_skip2
	s_setprio 1

.LBB0_337:
	s_or_b64 exec, exec, s[6:7]
	s_waitcnt vmcnt(0)
	v_lshlrev_b32_e32 v0, 15, v186
	s_lshl_b32 s2, s64, 22
	s_lshl_b32 s3, s75, 20
	v_and_b32_e32 v0, 0xffff0000, v0
	s_or_b32 s2, s2, s3
	v_lshl_add_u32 v0, v187, 12, v0
	v_and_b32_e32 v1, 1, v186
	s_add_u32 s2, s94, s2
	v_lshl_or_b32 v0, v1, 6, v0
	s_addc_u32 s3, s95, 0
	v_lshl_add_u32 v0, v188, 1, v0
	v_mov_b32_e32 v1, 0
	v_lshl_add_u64 v[2:3], s[2:3], 0, v[0:1]
	v_lshlrev_b32_e32 v0, 15, v189
	s_mov_b64 s[6:7], 0xf280080
	v_and_b32_e32 v0, 0xffff0000, v0
	v_lshl_add_u64 v[40:41], v[2:3], 0, s[6:7]
	v_lshl_add_u32 v0, v190, 12, v0
	v_and_b32_e32 v2, 1, v189
	v_lshl_or_b32 v0, v2, 6, v0
	v_lshl_add_u32 v0, v191, 1, v0
	v_lshl_add_u64 v[2:3], s[2:3], 0, v[0:1]
	v_lshl_add_u64 v[42:43], v[2:3], 0, s[6:7]
	s_add_u32 s6, s94, s8
	s_addc_u32 s7, s95, 0
	s_add_u32 s19, s6, 0x200100
	s_addc_u32 s20, s7, 0
	s_add_i32 s40, 0, 0x10000
	s_add_i32 s42, 0, 0x14000
	s_add_i32 s44, 0, 0x18000
	s_add_i32 s46, 0, 0x1c000
	v_add_u32_e32 v44, s40, v192
	v_add_u32_e32 v45, s42, v192
	s_add_i32 s40, s40, s66
	s_add_i32 s42, s42, s66
	v_add_u32_e32 v47, s44, v192
	v_add_u32_e32 v48, s46, v192
	s_add_i32 s44, s44, s66
	s_add_i32 s46, s46, s66
	s_mov_b32 s21, -2
	s_mov_b64 s[6:7], 0
	v_add_u32_e32 v46, 0, v193
	s_add_i32 s22, s12, 0xc000
	s_add_i32 s23, s12, 0xe000
	s_add_i32 s41, s40, 0x2000
	s_add_i32 s43, s42, 0x2000
	s_add_i32 s45, s44, 0x2000
	s_add_i32 s47, s46, 0x2000
	v_mov_b32_e32 v0, v1
	v_mov_b32_e32 v2, v1
	v_mov_b32_e32 v3, v1
	v_mov_b32_e32 v4, v1
	v_mov_b32_e32 v5, v1
	v_mov_b32_e32 v6, v1
	v_mov_b32_e32 v7, v1
	v_mov_b32_e32 v16, v1
	v_mov_b32_e32 v17, v1
	v_mov_b32_e32 v18, v1
	v_mov_b32_e32 v19, v1
	v_mov_b32_e32 v20, v1
	v_mov_b32_e32 v21, v1
	v_mov_b32_e32 v22, v1
	v_mov_b32_e32 v23, v1
	v_mov_b32_e32 v32, v1
	v_mov_b32_e32 v33, v1
	v_mov_b32_e32 v34, v1
	v_mov_b32_e32 v35, v1
	v_mov_b32_e32 v36, v1
	v_mov_b32_e32 v37, v1
	v_mov_b32_e32 v38, v1
	v_mov_b32_e32 v39, v1
	v_mov_b32_e32 v64, v1
	v_mov_b32_e32 v65, v1
	v_mov_b32_e32 v66, v1
	v_mov_b32_e32 v67, v1
	v_mov_b32_e32 v68, v1
	v_mov_b32_e32 v69, v1
	v_mov_b32_e32 v70, v1
	v_mov_b32_e32 v71, v1
	v_mov_b32_e32 v8, v1
	v_mov_b32_e32 v9, v1
	v_mov_b32_e32 v10, v1
	v_mov_b32_e32 v11, v1
	v_mov_b32_e32 v12, v1
	v_mov_b32_e32 v13, v1
	v_mov_b32_e32 v14, v1
	v_mov_b32_e32 v15, v1
	v_mov_b32_e32 v24, v1
	v_mov_b32_e32 v25, v1
	v_mov_b32_e32 v26, v1
	v_mov_b32_e32 v27, v1
	v_mov_b32_e32 v28, v1
	v_mov_b32_e32 v29, v1
	v_mov_b32_e32 v30, v1
	v_mov_b32_e32 v31, v1
	v_mov_b32_e32 v56, v1
	v_mov_b32_e32 v57, v1
	v_mov_b32_e32 v58, v1
	v_mov_b32_e32 v59, v1
	v_mov_b32_e32 v60, v1
	v_mov_b32_e32 v61, v1
	v_mov_b32_e32 v62, v1
	v_mov_b32_e32 v63, v1
	v_mov_b32_e32 v72, v1
	v_mov_b32_e32 v73, v1
	v_mov_b32_e32 v74, v1
	v_mov_b32_e32 v75, v1
	v_mov_b32_e32 v76, v1
	v_mov_b32_e32 v77, v1
	v_mov_b32_e32 v78, v1
	v_mov_b32_e32 v79, v1
	v_mov_b32_e32 v80, v1
	v_mov_b32_e32 v81, v1
	v_mov_b32_e32 v82, v1
	v_mov_b32_e32 v83, v1
	v_mov_b32_e32 v84, v1
	v_mov_b32_e32 v85, v1
	v_mov_b32_e32 v86, v1
	v_mov_b32_e32 v87, v1
	v_mov_b32_e32 v96, v1
	v_mov_b32_e32 v97, v1
	v_mov_b32_e32 v98, v1
	v_mov_b32_e32 v99, v1
	v_mov_b32_e32 v100, v1
	v_mov_b32_e32 v101, v1
	v_mov_b32_e32 v102, v1
	v_mov_b32_e32 v103, v1
	v_mov_b32_e32 v112, v1
	v_mov_b32_e32 v113, v1
	v_mov_b32_e32 v114, v1
	v_mov_b32_e32 v115, v1
	v_mov_b32_e32 v116, v1
	v_mov_b32_e32 v117, v1
	v_mov_b32_e32 v118, v1
	v_mov_b32_e32 v119, v1
	v_mov_b32_e32 v128, v1
	v_mov_b32_e32 v129, v1
	v_mov_b32_e32 v130, v1
	v_mov_b32_e32 v131, v1
	v_mov_b32_e32 v132, v1
	v_mov_b32_e32 v133, v1
	v_mov_b32_e32 v134, v1
	v_mov_b32_e32 v135, v1
	v_mov_b32_e32 v88, v1
	v_mov_b32_e32 v89, v1
	v_mov_b32_e32 v90, v1
	v_mov_b32_e32 v91, v1
	v_mov_b32_e32 v92, v1
	v_mov_b32_e32 v93, v1
	v_mov_b32_e32 v94, v1
	v_mov_b32_e32 v95, v1
	v_mov_b32_e32 v104, v1
	v_mov_b32_e32 v105, v1
	v_mov_b32_e32 v106, v1
	v_mov_b32_e32 v107, v1
	v_mov_b32_e32 v108, v1
	v_mov_b32_e32 v109, v1
	v_mov_b32_e32 v110, v1
	v_mov_b32_e32 v111, v1
	v_mov_b32_e32 v120, v1
	v_mov_b32_e32 v121, v1
	v_mov_b32_e32 v122, v1
	v_mov_b32_e32 v123, v1
	v_mov_b32_e32 v124, v1
	v_mov_b32_e32 v125, v1
	v_mov_b32_e32 v126, v1
	v_mov_b32_e32 v127, v1
	v_mov_b32_e32 v136, v1
	v_mov_b32_e32 v137, v1
	v_mov_b32_e32 v138, v1
	v_mov_b32_e32 v139, v1
	v_mov_b32_e32 v140, v1
	v_mov_b32_e32 v141, v1
	v_mov_b32_e32 v142, v1
	v_mov_b32_e32 v143, v1
	s_lshr_b32 s101, s88, 2
	s_cmp_lg_u32 s101, 0
	s_cbranch_scc1 .Lprio_skip3
	s_setprio 1

.LBB0_654:
	s_add_i32 s56, s56, 1
	s_lshl_b32 s2, s56, 5
	s_add_i32 s2, s2, s34
	s_cmp_lt_i32 s2, 32
	s_mov_b32 s20, s6
	s_cselect_b64 s[26:27], -1, 0
	s_ashr_i32 s6, s2, 2
	s_ashr_i32 s7, s6, 31
	s_lshl_b64 s[2:3], s[6:7], 20
	s_mov_b64 s[0:1], s[8:9]
	s_add_u32 s8, s35, s2
	s_addc_u32 s9, s36, s3
	s_and_b64 s[2:3], s[26:27], exec
	v_mov_b32_e32 v0, 0
	s_cselect_b32 s7, s9, s1
	s_cselect_b32 s57, s8, s0
	s_mov_b32 s58, -2
	s_mov_b64 s[2:3], 0x100
	s_waitcnt lgkmcnt(0)
	v_mov_b32_e32 v1, v0
	v_mov_b32_e32 v2, v0
	v_mov_b32_e32 v3, v0
	v_mov_b32_e32 v4, v0
	v_mov_b32_e32 v5, v0
	v_mov_b32_e32 v6, v0
	v_mov_b32_e32 v7, v0
	v_mov_b32_e32 v16, v0
	v_mov_b32_e32 v17, v0
	v_mov_b32_e32 v18, v0
	v_mov_b32_e32 v19, v0
	v_mov_b32_e32 v20, v0
	v_mov_b32_e32 v21, v0
	v_mov_b32_e32 v22, v0
	v_mov_b32_e32 v23, v0
	v_mov_b32_e32 v32, v0
	v_mov_b32_e32 v33, v0
	v_mov_b32_e32 v34, v0
	v_mov_b32_e32 v35, v0
	v_mov_b32_e32 v36, v0
	v_mov_b32_e32 v37, v0
	v_mov_b32_e32 v38, v0
	v_mov_b32_e32 v39, v0
	v_mov_b32_e32 v48, v0
	v_mov_b32_e32 v49, v0
	v_mov_b32_e32 v50, v0
	v_mov_b32_e32 v51, v0
	v_mov_b32_e32 v52, v0
	v_mov_b32_e32 v53, v0
	v_mov_b32_e32 v54, v0
	v_mov_b32_e32 v55, v0
	v_mov_b32_e32 v8, v0
	v_mov_b32_e32 v9, v0
	v_mov_b32_e32 v10, v0
	v_mov_b32_e32 v11, v0
	v_mov_b32_e32 v12, v0
	v_mov_b32_e32 v13, v0
	v_mov_b32_e32 v14, v0
	v_mov_b32_e32 v15, v0
	v_mov_b32_e32 v24, v0
	v_mov_b32_e32 v25, v0
	v_mov_b32_e32 v26, v0
	v_mov_b32_e32 v27, v0
	v_mov_b32_e32 v28, v0
	v_mov_b32_e32 v29, v0
	v_mov_b32_e32 v30, v0
	v_mov_b32_e32 v31, v0
	v_mov_b32_e32 v40, v0
	v_mov_b32_e32 v41, v0
	v_mov_b32_e32 v42, v0
	v_mov_b32_e32 v43, v0
	v_mov_b32_e32 v44, v0
	v_mov_b32_e32 v45, v0
	v_mov_b32_e32 v46, v0
	v_mov_b32_e32 v47, v0
	v_mov_b32_e32 v56, v0
	v_mov_b32_e32 v57, v0
	v_mov_b32_e32 v58, v0
	v_mov_b32_e32 v59, v0
	v_mov_b32_e32 v60, v0
	v_mov_b32_e32 v61, v0
	v_mov_b32_e32 v62, v0
	v_mov_b32_e32 v63, v0
	v_mov_b32_e32 v64, v0
	v_mov_b32_e32 v65, v0
	v_mov_b32_e32 v66, v0
	v_mov_b32_e32 v67, v0
	v_mov_b32_e32 v68, v0
	v_mov_b32_e32 v69, v0
	v_mov_b32_e32 v70, v0
	v_mov_b32_e32 v71, v0
	v_mov_b32_e32 v80, v0
	v_mov_b32_e32 v81, v0
	v_mov_b32_e32 v82, v0
	v_mov_b32_e32 v83, v0
	v_mov_b32_e32 v84, v0
	v_mov_b32_e32 v85, v0
	v_mov_b32_e32 v86, v0
	v_mov_b32_e32 v87, v0
	v_mov_b32_e32 v96, v0
	v_mov_b32_e32 v97, v0
	v_mov_b32_e32 v98, v0
	v_mov_b32_e32 v99, v0
	v_mov_b32_e32 v100, v0
	v_mov_b32_e32 v101, v0
	v_mov_b32_e32 v102, v0
	v_mov_b32_e32 v103, v0
	v_mov_b32_e32 v112, v0
	v_mov_b32_e32 v113, v0
	v_mov_b32_e32 v114, v0
	v_mov_b32_e32 v115, v0
	v_mov_b32_e32 v116, v0
	v_mov_b32_e32 v117, v0
	v_mov_b32_e32 v118, v0
	v_mov_b32_e32 v119, v0
	v_mov_b32_e32 v72, v0
	v_mov_b32_e32 v73, v0
	v_mov_b32_e32 v74, v0
	v_mov_b32_e32 v75, v0
	v_mov_b32_e32 v76, v0
	v_mov_b32_e32 v77, v0
	v_mov_b32_e32 v78, v0
	v_mov_b32_e32 v79, v0
	v_mov_b32_e32 v88, v0
	v_mov_b32_e32 v89, v0
	v_mov_b32_e32 v90, v0
	v_mov_b32_e32 v91, v0
	v_mov_b32_e32 v92, v0
	v_mov_b32_e32 v93, v0
	v_mov_b32_e32 v94, v0
	v_mov_b32_e32 v95, v0
	v_mov_b32_e32 v104, v0
	v_mov_b32_e32 v105, v0
	v_mov_b32_e32 v106, v0
	v_mov_b32_e32 v107, v0
	v_mov_b32_e32 v108, v0
	v_mov_b32_e32 v109, v0
	v_mov_b32_e32 v110, v0
	v_mov_b32_e32 v111, v0
	v_mov_b32_e32 v124, v0
	v_mov_b32_e32 v125, v0
	v_mov_b32_e32 v126, v0
	v_mov_b32_e32 v127, v0
	v_mov_b32_e32 v128, v0
	v_mov_b32_e32 v129, v0
	v_mov_b32_e32 v130, v0
	v_mov_b32_e32 v131, v0
	s_lshr_b32 s101, s88, 2
	s_cmp_lg_u32 s101, 0
	s_cbranch_scc1 .Lprio_skip4
	s_setprio 1

.LBB0_784:
	s_add_i32 s53, s53, 1
	s_mov_b64 s[38:39], s[10:11]
	s_mov_b32 s68, s4
	s_mov_b32 s10, s4
	s_lshl_b32 s4, s53, 5
	s_add_i32 s4, s4, s19
	s_cmp_lt_i32 s4, 32
	s_cselect_b64 s[34:35], -1, 0
	s_ashr_i32 s4, s4, 2
	s_mov_b64 s[36:37], s[8:9]
	s_and_b64 s[8:9], s[34:35], exec
	s_cselect_b32 s8, s42, s42
	s_cselect_b32 s10, s4, s10
	s_ashr_i32 s9, s8, 31
	s_lshl_b64 s[8:9], s[8:9], 20
	s_add_u32 s8, s43, s8
	s_addc_u32 s9, s44, s9
	s_and_b64 s[40:41], s[34:35], exec
	s_cselect_b32 s69, s9, s37
	s_cselect_b32 s70, s8, s36
	s_ashr_i32 s11, s10, 31
	s_lshl_b64 s[10:11], s[10:11], 20
	s_add_u32 s10, s45, s10
	s_addc_u32 s11, s46, s11
	s_and_b64 s[40:41], s[34:35], exec
	s_cselect_b32 s71, s11, s39
	s_cselect_b32 s72, s10, s38
	s_add_u32 s36, s36, 0x80080
	s_addc_u32 s37, s37, 0
	s_add_u32 s73, s38, 0x100
	s_addc_u32 s74, s39, 0
	s_mov_b32 s75, -2
	v_mov_b32_e32 v0, 0
	v_mov_b32_e32 v1, v137
	v_mov_b32_e32 v2, v137
	v_mov_b32_e32 v3, v137
	v_mov_b32_e32 v4, 0
	v_mov_b32_e32 v5, v137
	v_mov_b32_e32 v6, v137
	v_mov_b32_e32 v7, v137
	v_mov_b32_e32 v12, 0
	v_mov_b32_e32 v13, v137
	v_mov_b32_e32 v14, v137
	v_mov_b32_e32 v15, v137
	v_mov_b32_e32 v20, 0
	v_mov_b32_e32 v21, v137
	v_mov_b32_e32 v22, v137
	v_mov_b32_e32 v23, v137
	v_mov_b32_e32 v28, 0
	v_mov_b32_e32 v29, v137
	v_mov_b32_e32 v30, v137
	v_mov_b32_e32 v31, v137
	v_mov_b32_e32 v36, 0
	v_mov_b32_e32 v37, v137
	v_mov_b32_e32 v38, v137
	v_mov_b32_e32 v39, v137
	v_mov_b32_e32 v44, 0
	v_mov_b32_e32 v45, v137
	v_mov_b32_e32 v46, v137
	v_mov_b32_e32 v47, v137
	v_mov_b32_e32 v52, 0
	v_mov_b32_e32 v53, v137
	v_mov_b32_e32 v54, v137
	v_mov_b32_e32 v55, v137
	v_mov_b32_e32 v8, 0
	v_mov_b32_e32 v9, v137
	v_mov_b32_e32 v10, v137
	v_mov_b32_e32 v11, v137
	v_mov_b32_e32 v16, 0
	v_mov_b32_e32 v17, v137
	v_mov_b32_e32 v18, v137
	v_mov_b32_e32 v19, v137
	v_mov_b32_e32 v24, 0
	v_mov_b32_e32 v25, v137
	v_mov_b32_e32 v26, v137
	v_mov_b32_e32 v27, v137
	v_mov_b32_e32 v32, 0
	v_mov_b32_e32 v33, v137
	v_mov_b32_e32 v34, v137
	v_mov_b32_e32 v35, v137
	v_mov_b32_e32 v40, 0
	v_mov_b32_e32 v41, v137
	v_mov_b32_e32 v42, v137
	v_mov_b32_e32 v43, v137
	v_mov_b32_e32 v48, 0
	v_mov_b32_e32 v49, v137
	v_mov_b32_e32 v50, v137
	v_mov_b32_e32 v51, v137
	v_mov_b32_e32 v56, 0
	v_mov_b32_e32 v57, v137
	v_mov_b32_e32 v58, v137
	v_mov_b32_e32 v59, v137
	v_mov_b32_e32 v60, 0
	v_mov_b32_e32 v61, v137
	v_mov_b32_e32 v62, v137
	v_mov_b32_e32 v63, v137
	v_mov_b32_e32 v64, 0
	v_mov_b32_e32 v65, v137
	v_mov_b32_e32 v66, v137
	v_mov_b32_e32 v67, v137
	v_mov_b32_e32 v68, 0
	v_mov_b32_e32 v69, v137
	v_mov_b32_e32 v70, v137
	v_mov_b32_e32 v71, v137
	v_mov_b32_e32 v76, 0
	v_mov_b32_e32 v77, v137
	v_mov_b32_e32 v78, v137
	v_mov_b32_e32 v79, v137
	v_mov_b32_e32 v84, 0
	v_mov_b32_e32 v85, v137
	v_mov_b32_e32 v86, v137
	v_mov_b32_e32 v87, v137
	v_mov_b32_e32 v92, 0
	v_mov_b32_e32 v93, v137
	v_mov_b32_e32 v94, v137
	v_mov_b32_e32 v95, v137
	v_mov_b32_e32 v100, 0
	v_mov_b32_e32 v101, v137
	v_mov_b32_e32 v102, v137
	v_mov_b32_e32 v103, v137
	v_mov_b32_e32 v108, 0
	v_mov_b32_e32 v109, v137
	v_mov_b32_e32 v110, v137
	v_mov_b32_e32 v111, v137
	v_mov_b32_e32 v116, 0
	v_mov_b32_e32 v117, v137
	v_mov_b32_e32 v118, v137
	v_mov_b32_e32 v119, v137
	v_mov_b32_e32 v72, 0
	v_mov_b32_e32 v73, v137
	v_mov_b32_e32 v74, v137
	v_mov_b32_e32 v75, v137
	v_mov_b32_e32 v80, 0
	v_mov_b32_e32 v81, v137
	v_mov_b32_e32 v82, v137
	v_mov_b32_e32 v83, v137
	v_mov_b32_e32 v88, 0
	v_mov_b32_e32 v89, v137
	v_mov_b32_e32 v90, v137
	v_mov_b32_e32 v91, v137
	v_mov_b32_e32 v96, 0
	v_mov_b32_e32 v97, v137
	v_mov_b32_e32 v98, v137
	v_mov_b32_e32 v99, v137
	v_mov_b32_e32 v104, 0
	v_mov_b32_e32 v105, v137
	v_mov_b32_e32 v106, v137
	v_mov_b32_e32 v107, v137
	v_mov_b32_e32 v112, 0
	v_mov_b32_e32 v113, v137
	v_mov_b32_e32 v114, v137
	v_mov_b32_e32 v115, v137
	v_mov_b32_e32 v120, 0
	v_mov_b32_e32 v121, v137
	v_mov_b32_e32 v122, v137
	v_mov_b32_e32 v123, v137
	v_mov_b32_e32 v124, 0
	v_mov_b32_e32 v125, v137
	v_mov_b32_e32 v126, v137
	v_mov_b32_e32 v127, v137
	s_lshr_b32 s101, s88, 2
	s_cmp_lg_u32 s101, 0
	s_cbranch_scc1 .Lprio_skip5
	s_setprio 1

.LBB0_1083:
	s_add_i32 s52, s52, 1
	s_mov_b64 s[36:37], s[10:11]
	s_mov_b32 s67, s4
	s_mov_b32 s10, s4
	s_lshl_b32 s4, s52, 5
	s_add_i32 s4, s4, s40
	s_cmpk_lt_i32 s4, 0x80
	s_cselect_b64 s[34:35], -1, 0
	s_ashr_i32 s4, s4, 2
	s_mov_b64 s[0:1], s[8:9]
	s_and_b64 s[8:9], s[34:35], exec
	s_cselect_b32 s8, s41, s41
	s_cselect_b32 s10, s4, s10
	s_ashr_i32 s9, s8, 31
	s_lshl_b64 s[8:9], s[8:9], 20
	s_add_u32 s8, s42, s8
	s_addc_u32 s9, s43, s9
	s_and_b64 s[38:39], s[34:35], exec
	s_cselect_b32 s68, s9, s1
	s_cselect_b32 s69, s8, s0
	s_ashr_i32 s11, s10, 31
	s_lshl_b64 s[10:11], s[10:11], 20
	s_add_u32 s10, s44, s10
	s_addc_u32 s11, s45, s11
	s_and_b64 s[38:39], s[34:35], exec
	s_cselect_b32 s70, s11, s37
	s_cselect_b32 s71, s10, s36
	s_add_u32 s0, s0, 0x80080
	s_addc_u32 s1, s1, 0
	s_add_u32 s72, s36, 0x100
	s_addc_u32 s73, s37, 0
	s_mov_b32 s74, -2
	v_mov_b32_e32 v0, 0
	v_mov_b32_e32 v1, v137
	v_mov_b32_e32 v2, v137
	v_mov_b32_e32 v3, v137
	v_mov_b32_e32 v4, 0
	v_mov_b32_e32 v5, v137
	v_mov_b32_e32 v6, v137
	v_mov_b32_e32 v7, v137
	v_mov_b32_e32 v16, 0
	v_mov_b32_e32 v17, v137
	v_mov_b32_e32 v18, v137
	v_mov_b32_e32 v19, v137
	v_mov_b32_e32 v20, 0
	v_mov_b32_e32 v21, v137
	v_mov_b32_e32 v22, v137
	v_mov_b32_e32 v23, v137
	v_mov_b32_e32 v32, 0
	v_mov_b32_e32 v33, v137
	v_mov_b32_e32 v34, v137
	v_mov_b32_e32 v35, v137
	v_mov_b32_e32 v36, 0
	v_mov_b32_e32 v37, v137
	v_mov_b32_e32 v38, v137
	v_mov_b32_e32 v39, v137
	v_mov_b32_e32 v48, 0
	v_mov_b32_e32 v49, v137
	v_mov_b32_e32 v50, v137
	v_mov_b32_e32 v51, v137
	v_mov_b32_e32 v52, 0
	v_mov_b32_e32 v53, v137
	v_mov_b32_e32 v54, v137
	v_mov_b32_e32 v55, v137
	v_mov_b32_e32 v8, 0
	v_mov_b32_e32 v9, v137
	v_mov_b32_e32 v10, v137
	v_mov_b32_e32 v11, v137
	v_mov_b32_e32 v12, 0
	v_mov_b32_e32 v13, v137
	v_mov_b32_e32 v14, v137
	v_mov_b32_e32 v15, v137
	v_mov_b32_e32 v24, 0
	v_mov_b32_e32 v25, v137
	v_mov_b32_e32 v26, v137
	v_mov_b32_e32 v27, v137
	v_mov_b32_e32 v28, 0
	v_mov_b32_e32 v29, v137
	v_mov_b32_e32 v30, v137
	v_mov_b32_e32 v31, v137
	v_mov_b32_e32 v40, 0
	v_mov_b32_e32 v41, v137
	v_mov_b32_e32 v42, v137
	v_mov_b32_e32 v43, v137
	v_mov_b32_e32 v44, 0
	v_mov_b32_e32 v45, v137
	v_mov_b32_e32 v46, v137
	v_mov_b32_e32 v47, v137
	v_mov_b32_e32 v56, 0
	v_mov_b32_e32 v57, v137
	v_mov_b32_e32 v58, v137
	v_mov_b32_e32 v59, v137
	v_mov_b32_e32 v60, 0
	v_mov_b32_e32 v61, v137
	v_mov_b32_e32 v62, v137
	v_mov_b32_e32 v63, v137
	v_mov_b32_e32 v64, 0
	v_mov_b32_e32 v65, v137
	v_mov_b32_e32 v66, v137
	v_mov_b32_e32 v67, v137
	v_mov_b32_e32 v68, 0
	v_mov_b32_e32 v69, v137
	v_mov_b32_e32 v70, v137
	v_mov_b32_e32 v71, v137
	v_mov_b32_e32 v80, 0
	v_mov_b32_e32 v81, v137
	v_mov_b32_e32 v82, v137
	v_mov_b32_e32 v83, v137
	v_mov_b32_e32 v84, 0
	v_mov_b32_e32 v85, v137
	v_mov_b32_e32 v86, v137
	v_mov_b32_e32 v87, v137
	v_mov_b32_e32 v96, 0
	v_mov_b32_e32 v97, v137
	v_mov_b32_e32 v98, v137
	v_mov_b32_e32 v99, v137
	v_mov_b32_e32 v100, 0
	v_mov_b32_e32 v101, v137
	v_mov_b32_e32 v102, v137
	v_mov_b32_e32 v103, v137
	v_mov_b32_e32 v112, 0
	v_mov_b32_e32 v113, v137
	v_mov_b32_e32 v114, v137
	v_mov_b32_e32 v115, v137
	v_mov_b32_e32 v116, 0
	v_mov_b32_e32 v117, v137
	v_mov_b32_e32 v118, v137
	v_mov_b32_e32 v119, v137
	v_mov_b32_e32 v72, 0
	v_mov_b32_e32 v73, v137
	v_mov_b32_e32 v74, v137
	v_mov_b32_e32 v75, v137
	v_mov_b32_e32 v76, 0
	v_mov_b32_e32 v77, v137
	v_mov_b32_e32 v78, v137
	v_mov_b32_e32 v79, v137
	v_mov_b32_e32 v88, 0
	v_mov_b32_e32 v89, v137
	v_mov_b32_e32 v90, v137
	v_mov_b32_e32 v91, v137
	v_mov_b32_e32 v92, 0
	v_mov_b32_e32 v93, v137
	v_mov_b32_e32 v94, v137
	v_mov_b32_e32 v95, v137
	v_mov_b32_e32 v104, 0
	v_mov_b32_e32 v105, v137
	v_mov_b32_e32 v106, v137
	v_mov_b32_e32 v107, v137
	v_mov_b32_e32 v108, 0
	v_mov_b32_e32 v109, v137
	v_mov_b32_e32 v110, v137
	v_mov_b32_e32 v111, v137
	v_mov_b32_e32 v120, 0
	v_mov_b32_e32 v121, v137
	v_mov_b32_e32 v122, v137
	v_mov_b32_e32 v123, v137
	v_mov_b32_e32 v124, 0
	v_mov_b32_e32 v125, v137
	v_mov_b32_e32 v126, v137
	v_mov_b32_e32 v127, v137
	s_lshr_b32 s101, s88, 2
	s_cmp_lg_u32 s101, 0
	s_cbranch_scc1 .Lprio_skip7
	s_setprio 1

.LBB0_1193:
	s_add_i32 s56, s56, 1
	s_lshl_b32 s2, s56, 5
	s_add_i32 s2, s2, s34
	s_cmp_lt_i32 s2, 32
	s_mov_b32 s20, s6
	s_cselect_b64 s[26:27], -1, 0
	s_ashr_i32 s6, s2, 2
	s_ashr_i32 s7, s6, 31
	s_lshl_b64 s[2:3], s[6:7], 22
	s_mov_b64 s[0:1], s[8:9]
	s_add_u32 s8, s35, s2
	s_addc_u32 s9, s36, s3
	s_and_b64 s[2:3], s[26:27], exec
	v_mov_b32_e32 v0, 0
	s_cselect_b32 s7, s9, s1
	s_cselect_b32 s57, s8, s0
	s_mov_b32 s58, -2
	s_mov_b64 s[2:3], 0x100
	s_waitcnt lgkmcnt(0)
	v_mov_b32_e32 v1, v0
	v_mov_b32_e32 v2, v0
	v_mov_b32_e32 v3, v0
	v_mov_b32_e32 v4, v0
	v_mov_b32_e32 v5, v0
	v_mov_b32_e32 v6, v0
	v_mov_b32_e32 v7, v0
	v_mov_b32_e32 v16, v0
	v_mov_b32_e32 v17, v0
	v_mov_b32_e32 v18, v0
	v_mov_b32_e32 v19, v0
	v_mov_b32_e32 v20, v0
	v_mov_b32_e32 v21, v0
	v_mov_b32_e32 v22, v0
	v_mov_b32_e32 v23, v0
	v_mov_b32_e32 v32, v0
	v_mov_b32_e32 v33, v0
	v_mov_b32_e32 v34, v0
	v_mov_b32_e32 v35, v0
	v_mov_b32_e32 v36, v0
	v_mov_b32_e32 v37, v0
	v_mov_b32_e32 v38, v0
	v_mov_b32_e32 v39, v0
	v_mov_b32_e32 v48, v0
	v_mov_b32_e32 v49, v0
	v_mov_b32_e32 v50, v0
	v_mov_b32_e32 v51, v0
	v_mov_b32_e32 v52, v0
	v_mov_b32_e32 v53, v0
	v_mov_b32_e32 v54, v0
	v_mov_b32_e32 v55, v0
	v_mov_b32_e32 v8, v0
	v_mov_b32_e32 v9, v0
	v_mov_b32_e32 v10, v0
	v_mov_b32_e32 v11, v0
	v_mov_b32_e32 v12, v0
	v_mov_b32_e32 v13, v0
	v_mov_b32_e32 v14, v0
	v_mov_b32_e32 v15, v0
	v_mov_b32_e32 v24, v0
	v_mov_b32_e32 v25, v0
	v_mov_b32_e32 v26, v0
	v_mov_b32_e32 v27, v0
	v_mov_b32_e32 v28, v0
	v_mov_b32_e32 v29, v0
	v_mov_b32_e32 v30, v0
	v_mov_b32_e32 v31, v0
	v_mov_b32_e32 v40, v0
	v_mov_b32_e32 v41, v0
	v_mov_b32_e32 v42, v0
	v_mov_b32_e32 v43, v0
	v_mov_b32_e32 v44, v0
	v_mov_b32_e32 v45, v0
	v_mov_b32_e32 v46, v0
	v_mov_b32_e32 v47, v0
	v_mov_b32_e32 v56, v0
	v_mov_b32_e32 v57, v0
	v_mov_b32_e32 v58, v0
	v_mov_b32_e32 v59, v0
	v_mov_b32_e32 v60, v0
	v_mov_b32_e32 v61, v0
	v_mov_b32_e32 v62, v0
	v_mov_b32_e32 v63, v0
	v_mov_b32_e32 v64, v0
	v_mov_b32_e32 v65, v0
	v_mov_b32_e32 v66, v0
	v_mov_b32_e32 v67, v0
	v_mov_b32_e32 v68, v0
	v_mov_b32_e32 v69, v0
	v_mov_b32_e32 v70, v0
	v_mov_b32_e32 v71, v0
	v_mov_b32_e32 v80, v0
	v_mov_b32_e32 v81, v0
	v_mov_b32_e32 v82, v0
	v_mov_b32_e32 v83, v0
	v_mov_b32_e32 v84, v0
	v_mov_b32_e32 v85, v0
	v_mov_b32_e32 v86, v0
	v_mov_b32_e32 v87, v0
	v_mov_b32_e32 v96, v0
	v_mov_b32_e32 v97, v0
	v_mov_b32_e32 v98, v0
	v_mov_b32_e32 v99, v0
	v_mov_b32_e32 v100, v0
	v_mov_b32_e32 v101, v0
	v_mov_b32_e32 v102, v0
	v_mov_b32_e32 v103, v0
	v_mov_b32_e32 v112, v0
	v_mov_b32_e32 v113, v0
	v_mov_b32_e32 v114, v0
	v_mov_b32_e32 v115, v0
	v_mov_b32_e32 v116, v0
	v_mov_b32_e32 v117, v0
	v_mov_b32_e32 v118, v0
	v_mov_b32_e32 v119, v0
	v_mov_b32_e32 v72, v0
	v_mov_b32_e32 v73, v0
	v_mov_b32_e32 v74, v0
	v_mov_b32_e32 v75, v0
	v_mov_b32_e32 v76, v0
	v_mov_b32_e32 v77, v0
	v_mov_b32_e32 v78, v0
	v_mov_b32_e32 v79, v0
	v_mov_b32_e32 v88, v0
	v_mov_b32_e32 v89, v0
	v_mov_b32_e32 v90, v0
	v_mov_b32_e32 v91, v0
	v_mov_b32_e32 v92, v0
	v_mov_b32_e32 v93, v0
	v_mov_b32_e32 v94, v0
	v_mov_b32_e32 v95, v0
	v_mov_b32_e32 v104, v0
	v_mov_b32_e32 v105, v0
	v_mov_b32_e32 v106, v0
	v_mov_b32_e32 v107, v0
	v_mov_b32_e32 v108, v0
	v_mov_b32_e32 v109, v0
	v_mov_b32_e32 v110, v0
	v_mov_b32_e32 v111, v0
	v_mov_b32_e32 v124, v0
	v_mov_b32_e32 v125, v0
	v_mov_b32_e32 v126, v0
	v_mov_b32_e32 v127, v0
	v_mov_b32_e32 v128, v0
	v_mov_b32_e32 v129, v0
	v_mov_b32_e32 v130, v0
	v_mov_b32_e32 v131, v0
	s_lshr_b32 s101, s88, 2
	s_cmp_lg_u32 s101, 0
	s_cbranch_scc1 .Lprio_skip8
	s_setprio 1

.LBB0_1323:
	s_add_i32 s50, s50, 1
	s_mov_b64 s[34:35], s[0:1]
	s_lshl_b32 s0, s50, 5
	s_add_i32 s0, s0, s38
	s_cmp_lt_i32 s0, 32
	s_mov_b64 s[30:31], s[6:7]
	s_mov_b32 s65, s4
	s_mov_b32 s6, s4
	s_cselect_b64 s[28:29], -1, 0
	s_ashr_i32 s4, s0, 2
	s_and_b64 s[0:1], s[28:29], exec
	s_cselect_b32 s0, s4, s6
	s_cselect_b32 s6, s39, s39
	s_ashr_i32 s7, s6, 31
	s_lshl_b64 s[6:7], s[6:7], 20
	s_add_u32 s6, s40, s6
	s_addc_u32 s7, s41, s7
	s_and_b64 s[36:37], s[28:29], exec
	s_cselect_b32 s66, s7, s31
	s_cselect_b32 s67, s6, s30
	s_ashr_i32 s1, s0, 31
	s_lshl_b64 s[0:1], s[0:1], 20
	s_add_u32 s0, s42, s0
	s_addc_u32 s1, s43, s1
	s_and_b64 s[36:37], s[28:29], exec
	s_cselect_b32 s68, s1, s35
	s_cselect_b32 s69, s0, s34
	s_add_u32 s30, s30, 0x80080
	s_addc_u32 s31, s31, 0
	s_add_u32 s70, s34, 0x100
	s_addc_u32 s71, s35, 0
	s_mov_b32 s72, -2
	v_mov_b32_e32 v0, 0
	v_mov_b32_e32 v1, v137
	v_mov_b32_e32 v2, v137
	v_mov_b32_e32 v3, v137
	v_mov_b32_e32 v4, 0
	v_mov_b32_e32 v5, v137
	v_mov_b32_e32 v6, v137
	v_mov_b32_e32 v7, v137
	v_mov_b32_e32 v12, 0
	v_mov_b32_e32 v13, v137
	v_mov_b32_e32 v14, v137
	v_mov_b32_e32 v15, v137
	v_mov_b32_e32 v20, 0
	v_mov_b32_e32 v21, v137
	v_mov_b32_e32 v22, v137
	v_mov_b32_e32 v23, v137
	v_mov_b32_e32 v28, 0
	v_mov_b32_e32 v29, v137
	v_mov_b32_e32 v30, v137
	v_mov_b32_e32 v31, v137
	v_mov_b32_e32 v36, 0
	v_mov_b32_e32 v37, v137
	v_mov_b32_e32 v38, v137
	v_mov_b32_e32 v39, v137
	v_mov_b32_e32 v44, 0
	v_mov_b32_e32 v45, v137
	v_mov_b32_e32 v46, v137
	v_mov_b32_e32 v47, v137
	v_mov_b32_e32 v52, 0
	v_mov_b32_e32 v53, v137
	v_mov_b32_e32 v54, v137
	v_mov_b32_e32 v55, v137
	v_mov_b32_e32 v8, 0
	v_mov_b32_e32 v9, v137
	v_mov_b32_e32 v10, v137
	v_mov_b32_e32 v11, v137
	v_mov_b32_e32 v16, 0
	v_mov_b32_e32 v17, v137
	v_mov_b32_e32 v18, v137
	v_mov_b32_e32 v19, v137
	v_mov_b32_e32 v24, 0
	v_mov_b32_e32 v25, v137
	v_mov_b32_e32 v26, v137
	v_mov_b32_e32 v27, v137
	v_mov_b32_e32 v32, 0
	v_mov_b32_e32 v33, v137
	v_mov_b32_e32 v34, v137
	v_mov_b32_e32 v35, v137
	v_mov_b32_e32 v40, 0
	v_mov_b32_e32 v41, v137
	v_mov_b32_e32 v42, v137
	v_mov_b32_e32 v43, v137
	v_mov_b32_e32 v48, 0
	v_mov_b32_e32 v49, v137
	v_mov_b32_e32 v50, v137
	v_mov_b32_e32 v51, v137
	v_mov_b32_e32 v56, 0
	v_mov_b32_e32 v57, v137
	v_mov_b32_e32 v58, v137
	v_mov_b32_e32 v59, v137
	v_mov_b32_e32 v60, 0
	v_mov_b32_e32 v61, v137
	v_mov_b32_e32 v62, v137
	v_mov_b32_e32 v63, v137
	v_mov_b32_e32 v64, 0
	v_mov_b32_e32 v65, v137
	v_mov_b32_e32 v66, v137
	v_mov_b32_e32 v67, v137
	v_mov_b32_e32 v68, 0
	v_mov_b32_e32 v69, v137
	v_mov_b32_e32 v70, v137
	v_mov_b32_e32 v71, v137
	v_mov_b32_e32 v76, 0
	v_mov_b32_e32 v77, v137
	v_mov_b32_e32 v78, v137
	v_mov_b32_e32 v79, v137
	v_mov_b32_e32 v84, 0
	v_mov_b32_e32 v85, v137
	v_mov_b32_e32 v86, v137
	v_mov_b32_e32 v87, v137
	v_mov_b32_e32 v92, 0
	v_mov_b32_e32 v93, v137
	v_mov_b32_e32 v94, v137
	v_mov_b32_e32 v95, v137
	v_mov_b32_e32 v100, 0
	v_mov_b32_e32 v101, v137
	v_mov_b32_e32 v102, v137
	v_mov_b32_e32 v103, v137
	v_mov_b32_e32 v108, 0
	v_mov_b32_e32 v109, v137
	v_mov_b32_e32 v110, v137
	v_mov_b32_e32 v111, v137
	v_mov_b32_e32 v116, 0
	v_mov_b32_e32 v117, v137
	v_mov_b32_e32 v118, v137
	v_mov_b32_e32 v119, v137
	v_mov_b32_e32 v72, 0
	v_mov_b32_e32 v73, v137
	v_mov_b32_e32 v74, v137
	v_mov_b32_e32 v75, v137
	v_mov_b32_e32 v80, 0
	v_mov_b32_e32 v81, v137
	v_mov_b32_e32 v82, v137
	v_mov_b32_e32 v83, v137
	v_mov_b32_e32 v88, 0
	v_mov_b32_e32 v89, v137
	v_mov_b32_e32 v90, v137
	v_mov_b32_e32 v91, v137
	v_mov_b32_e32 v96, 0
	v_mov_b32_e32 v97, v137
	v_mov_b32_e32 v98, v137
	v_mov_b32_e32 v99, v137
	v_mov_b32_e32 v104, 0
	v_mov_b32_e32 v105, v137
	v_mov_b32_e32 v106, v137
	v_mov_b32_e32 v107, v137
	v_mov_b32_e32 v112, 0
	v_mov_b32_e32 v113, v137
	v_mov_b32_e32 v114, v137
	v_mov_b32_e32 v115, v137
	v_mov_b32_e32 v120, 0
	v_mov_b32_e32 v121, v137
	v_mov_b32_e32 v122, v137
	v_mov_b32_e32 v123, v137
	v_mov_b32_e32 v124, 0
	v_mov_b32_e32 v125, v137
	v_mov_b32_e32 v126, v137
	v_mov_b32_e32 v127, v137
	s_lshr_b32 s101, s88, 2
	s_cmp_lg_u32 s101, 0
	s_cbranch_scc1 .Lprio_skip9
	s_setprio 1

.LBB0_1525:
	s_add_i32 s51, s51, 1
	s_mov_b64 s[0:1], s[10:11]
	s_mov_b32 s22, s6
	s_mov_b32 s10, s6
	s_lshl_b32 s6, s51, 5
	s_add_i32 s6, s6, s34
	s_cmp_lt_i32 s6, 64
	s_cselect_b64 s[28:29], -1, 0
	s_ashr_i32 s6, s6, 2
	s_mov_b64 s[2:3], s[8:9]
	s_and_b64 s[8:9], s[28:29], exec
	s_cselect_b32 s8, s6, s10
	s_cselect_b32 s10, s40, s40
	s_ashr_i32 s11, s10, 31
	s_lshl_b64 s[10:11], s[10:11], 20
	s_add_u32 s10, s35, s10
	s_addc_u32 s11, s36, s11
	s_and_b64 s[30:31], s[28:29], exec
	s_cselect_b32 s52, s11, s1
	s_cselect_b32 s53, s10, s0
	s_ashr_i32 s9, s8, 31
	s_lshl_b64 s[8:9], s[8:9], 20
	s_add_u32 s8, s37, s8
	s_addc_u32 s9, s38, s9
	s_and_b64 s[30:31], s[28:29], exec
	s_cselect_b32 s54, s9, s3
	s_cselect_b32 s55, s8, s2
	s_add_u32 s0, s0, 0x80080
	s_addc_u32 s1, s1, 0
	s_add_u32 s56, s2, 0x100
	v_mov_b32_e32 v4, 0
	s_addc_u32 s57, s3, 0
	s_mov_b32 s58, -2
	v_mov_b32_e32 v5, v4
	v_mov_b32_e32 v6, v4
	v_mov_b32_e32 v7, v4
	v_mov_b32_e32 v0, v4
	s_waitcnt lgkmcnt(0)
	v_mov_b32_e32 v1, v4
	v_mov_b32_e32 v2, v4
	v_mov_b32_e32 v3, v4
	v_mov_b32_e32 v20, v4
	v_mov_b32_e32 v21, v4
	v_mov_b32_e32 v22, v4
	v_mov_b32_e32 v23, v4
	v_mov_b32_e32 v16, v4
	v_mov_b32_e32 v17, v4
	v_mov_b32_e32 v18, v4
	v_mov_b32_e32 v19, v4
	v_mov_b32_e32 v36, v4
	v_mov_b32_e32 v37, v4
	v_mov_b32_e32 v38, v4
	v_mov_b32_e32 v39, v4
	v_mov_b32_e32 v32, v4
	v_mov_b32_e32 v33, v4
	v_mov_b32_e32 v34, v4
	v_mov_b32_e32 v35, v4
	v_mov_b32_e32 v52, v4
	v_mov_b32_e32 v53, v4
	v_mov_b32_e32 v54, v4
	v_mov_b32_e32 v55, v4
	v_mov_b32_e32 v48, v4
	v_mov_b32_e32 v49, v4
	v_mov_b32_e32 v50, v4
	v_mov_b32_e32 v51, v4
	v_mov_b32_e32 v12, v4
	v_mov_b32_e32 v13, v4
	v_mov_b32_e32 v14, v4
	v_mov_b32_e32 v15, v4
	v_mov_b32_e32 v8, v4
	v_mov_b32_e32 v9, v4
	v_mov_b32_e32 v10, v4
	v_mov_b32_e32 v11, v4
	v_mov_b32_e32 v28, v4
	v_mov_b32_e32 v29, v4
	v_mov_b32_e32 v30, v4
	v_mov_b32_e32 v31, v4
	v_mov_b32_e32 v24, v4
	v_mov_b32_e32 v25, v4
	v_mov_b32_e32 v26, v4
	v_mov_b32_e32 v27, v4
	v_mov_b32_e32 v44, v4
	v_mov_b32_e32 v45, v4
	v_mov_b32_e32 v46, v4
	v_mov_b32_e32 v47, v4
	v_mov_b32_e32 v40, v4
	v_mov_b32_e32 v41, v4
	v_mov_b32_e32 v42, v4
	v_mov_b32_e32 v43, v4
	v_mov_b32_e32 v60, v4
	v_mov_b32_e32 v61, v4
	v_mov_b32_e32 v62, v4
	v_mov_b32_e32 v63, v4
	v_mov_b32_e32 v56, v4
	v_mov_b32_e32 v57, v4
	v_mov_b32_e32 v58, v4
	v_mov_b32_e32 v59, v4
	v_mov_b32_e32 v68, v4
	v_mov_b32_e32 v69, v4
	v_mov_b32_e32 v70, v4
	v_mov_b32_e32 v71, v4
	v_mov_b32_e32 v64, v4
	v_mov_b32_e32 v65, v4
	v_mov_b32_e32 v66, v4
	v_mov_b32_e32 v67, v4
	v_mov_b32_e32 v96, v4
	v_mov_b32_e32 v97, v4
	v_mov_b32_e32 v98, v4
	v_mov_b32_e32 v99, v4
	v_mov_b32_e32 v88, v4
	v_mov_b32_e32 v89, v4
	v_mov_b32_e32 v90, v4
	v_mov_b32_e32 v91, v4
	v_mov_b32_e32 v116, v4
	v_mov_b32_e32 v117, v4
	v_mov_b32_e32 v118, v4
	v_mov_b32_e32 v119, v4
	v_mov_b32_e32 v112, v4
	v_mov_b32_e32 v113, v4
	v_mov_b32_e32 v114, v4
	v_mov_b32_e32 v115, v4
	v_mov_b32_e32 v132, v4
	v_mov_b32_e32 v133, v4
	v_mov_b32_e32 v134, v4
	v_mov_b32_e32 v135, v4
	v_mov_b32_e32 v128, v4
	v_mov_b32_e32 v129, v4
	v_mov_b32_e32 v130, v4
	v_mov_b32_e32 v131, v4
	v_mov_b32_e32 v76, v4
	v_mov_b32_e32 v77, v4
	v_mov_b32_e32 v78, v4
	v_mov_b32_e32 v79, v4
	v_mov_b32_e32 v72, v4
	v_mov_b32_e32 v73, v4
	v_mov_b32_e32 v74, v4
	v_mov_b32_e32 v75, v4
	v_mov_b32_e32 v108, v4
	v_mov_b32_e32 v109, v4
	v_mov_b32_e32 v110, v4
	v_mov_b32_e32 v111, v4
	v_mov_b32_e32 v104, v4
	v_mov_b32_e32 v105, v4
	v_mov_b32_e32 v106, v4
	v_mov_b32_e32 v107, v4
	v_mov_b32_e32 v124, v4
	v_mov_b32_e32 v125, v4
	v_mov_b32_e32 v126, v4
	v_mov_b32_e32 v127, v4
	v_mov_b32_e32 v120, v4
	v_mov_b32_e32 v121, v4
	v_mov_b32_e32 v122, v4
	v_mov_b32_e32 v123, v4
	v_mov_b32_e32 v140, v4
	v_mov_b32_e32 v141, v4
	v_mov_b32_e32 v142, v4
	v_mov_b32_e32 v143, v4
	v_mov_b32_e32 v136, v4
	v_mov_b32_e32 v137, v4
	v_mov_b32_e32 v138, v4
	v_mov_b32_e32 v139, v4
	s_lshr_b32 s101, s88, 2
	s_cmp_lg_u32 s101, 0
	s_cbranch_scc1 .Lprio_skip10
	s_setprio 1

.LBB0_1824:
	s_add_i32 s56, s56, 1
	s_lshl_b32 s2, s56, 5
	s_add_i32 s2, s2, s34
	s_cmp_lt_i32 s2, 32
	s_mov_b32 s20, s4
	s_cselect_b64 s[26:27], -1, 0
	s_ashr_i32 s4, s2, 2
	s_ashr_i32 s5, s4, 31
	s_lshl_b64 s[2:3], s[4:5], 20
	s_mov_b64 s[0:1], s[8:9]
	s_add_u32 s8, s35, s2
	s_addc_u32 s9, s36, s3
	s_and_b64 s[2:3], s[26:27], exec
	v_mov_b32_e32 v0, 0
	s_cselect_b32 s5, s9, s1
	s_cselect_b32 s57, s8, s0
	s_mov_b32 s58, -2
	s_mov_b64 s[2:3], 0x100
	s_waitcnt lgkmcnt(0)
	v_mov_b32_e32 v1, v0
	v_mov_b32_e32 v2, v0
	v_mov_b32_e32 v3, v0
	v_mov_b32_e32 v4, v0
	v_mov_b32_e32 v5, v0
	v_mov_b32_e32 v6, v0
	v_mov_b32_e32 v7, v0
	v_mov_b32_e32 v16, v0
	v_mov_b32_e32 v17, v0
	v_mov_b32_e32 v18, v0
	v_mov_b32_e32 v19, v0
	v_mov_b32_e32 v20, v0
	v_mov_b32_e32 v21, v0
	v_mov_b32_e32 v22, v0
	v_mov_b32_e32 v23, v0
	v_mov_b32_e32 v32, v0
	v_mov_b32_e32 v33, v0
	v_mov_b32_e32 v34, v0
	v_mov_b32_e32 v35, v0
	v_mov_b32_e32 v36, v0
	v_mov_b32_e32 v37, v0
	v_mov_b32_e32 v38, v0
	v_mov_b32_e32 v39, v0
	v_mov_b32_e32 v48, v0
	v_mov_b32_e32 v49, v0
	v_mov_b32_e32 v50, v0
	v_mov_b32_e32 v51, v0
	v_mov_b32_e32 v52, v0
	v_mov_b32_e32 v53, v0
	v_mov_b32_e32 v54, v0
	v_mov_b32_e32 v55, v0
	v_mov_b32_e32 v8, v0
	v_mov_b32_e32 v9, v0
	v_mov_b32_e32 v10, v0
	v_mov_b32_e32 v11, v0
	v_mov_b32_e32 v12, v0
	v_mov_b32_e32 v13, v0
	v_mov_b32_e32 v14, v0
	v_mov_b32_e32 v15, v0
	v_mov_b32_e32 v24, v0
	v_mov_b32_e32 v25, v0
	v_mov_b32_e32 v26, v0
	v_mov_b32_e32 v27, v0
	v_mov_b32_e32 v28, v0
	v_mov_b32_e32 v29, v0
	v_mov_b32_e32 v30, v0
	v_mov_b32_e32 v31, v0
	v_mov_b32_e32 v40, v0
	v_mov_b32_e32 v41, v0
	v_mov_b32_e32 v42, v0
	v_mov_b32_e32 v43, v0
	v_mov_b32_e32 v44, v0
	v_mov_b32_e32 v45, v0
	v_mov_b32_e32 v46, v0
	v_mov_b32_e32 v47, v0
	v_mov_b32_e32 v56, v0
	v_mov_b32_e32 v57, v0
	v_mov_b32_e32 v58, v0
	v_mov_b32_e32 v59, v0
	v_mov_b32_e32 v60, v0
	v_mov_b32_e32 v61, v0
	v_mov_b32_e32 v62, v0
	v_mov_b32_e32 v63, v0
	v_mov_b32_e32 v64, v0
	v_mov_b32_e32 v65, v0
	v_mov_b32_e32 v66, v0
	v_mov_b32_e32 v67, v0
	v_mov_b32_e32 v68, v0
	v_mov_b32_e32 v69, v0
	v_mov_b32_e32 v70, v0
	v_mov_b32_e32 v71, v0
	v_mov_b32_e32 v80, v0
	v_mov_b32_e32 v81, v0
	v_mov_b32_e32 v82, v0
	v_mov_b32_e32 v83, v0
	v_mov_b32_e32 v84, v0
	v_mov_b32_e32 v85, v0
	v_mov_b32_e32 v86, v0
	v_mov_b32_e32 v87, v0
	v_mov_b32_e32 v96, v0
	v_mov_b32_e32 v97, v0
	v_mov_b32_e32 v98, v0
	v_mov_b32_e32 v99, v0
	v_mov_b32_e32 v100, v0
	v_mov_b32_e32 v101, v0
	v_mov_b32_e32 v102, v0
	v_mov_b32_e32 v103, v0
	v_mov_b32_e32 v112, v0
	v_mov_b32_e32 v113, v0
	v_mov_b32_e32 v114, v0
	v_mov_b32_e32 v115, v0
	v_mov_b32_e32 v116, v0
	v_mov_b32_e32 v117, v0
	v_mov_b32_e32 v118, v0
	v_mov_b32_e32 v119, v0
	v_mov_b32_e32 v72, v0
	v_mov_b32_e32 v73, v0
	v_mov_b32_e32 v74, v0
	v_mov_b32_e32 v75, v0
	v_mov_b32_e32 v76, v0
	v_mov_b32_e32 v77, v0
	v_mov_b32_e32 v78, v0
	v_mov_b32_e32 v79, v0
	v_mov_b32_e32 v88, v0
	v_mov_b32_e32 v89, v0
	v_mov_b32_e32 v90, v0
	v_mov_b32_e32 v91, v0
	v_mov_b32_e32 v92, v0
	v_mov_b32_e32 v93, v0
	v_mov_b32_e32 v94, v0
	v_mov_b32_e32 v95, v0
	v_mov_b32_e32 v104, v0
	v_mov_b32_e32 v105, v0
	v_mov_b32_e32 v106, v0
	v_mov_b32_e32 v107, v0
	v_mov_b32_e32 v108, v0
	v_mov_b32_e32 v109, v0
	v_mov_b32_e32 v110, v0
	v_mov_b32_e32 v111, v0
	v_mov_b32_e32 v124, v0
	v_mov_b32_e32 v125, v0
	v_mov_b32_e32 v126, v0
	v_mov_b32_e32 v127, v0
	v_mov_b32_e32 v128, v0
	v_mov_b32_e32 v129, v0
	v_mov_b32_e32 v130, v0
	v_mov_b32_e32 v131, v0
	s_lshr_b32 s101, s88, 2
	s_cmp_lg_u32 s101, 0
	s_cbranch_scc1 .Lprio_skip12
	s_setprio 1

.LBB0_1954:
	s_add_i32 s52, s52, 1
	s_mov_b64 s[36:37], s[10:11]
	s_mov_b32 s67, s6
	s_mov_b32 s10, s6
	s_lshl_b32 s6, s52, 5
	s_add_i32 s6, s6, s40
	s_cmpk_lt_i32 s6, 0x80
	s_cselect_b64 s[34:35], -1, 0
	s_ashr_i32 s6, s6, 2
	s_mov_b64 s[0:1], s[8:9]
	s_and_b64 s[8:9], s[34:35], exec
	s_cselect_b32 s8, s41, s41
	s_cselect_b32 s10, s6, s10
	s_ashr_i32 s9, s8, 31
	s_lshl_b64 s[8:9], s[8:9], 20
	s_add_u32 s8, s42, s8
	s_addc_u32 s9, s43, s9
	s_and_b64 s[38:39], s[34:35], exec
	s_cselect_b32 s68, s9, s1
	s_cselect_b32 s69, s8, s0
	s_ashr_i32 s11, s10, 31
	s_lshl_b64 s[10:11], s[10:11], 20
	s_add_u32 s10, s44, s10
	s_addc_u32 s11, s45, s11
	s_and_b64 s[38:39], s[34:35], exec
	s_cselect_b32 s70, s11, s37
	s_cselect_b32 s71, s10, s36
	s_add_u32 s0, s0, 0x80080
	s_addc_u32 s1, s1, 0
	s_add_u32 s72, s36, 0x100
	s_addc_u32 s73, s37, 0
	s_mov_b32 s74, -2
	v_mov_b32_e32 v0, 0
	v_mov_b32_e32 v1, v137
	v_mov_b32_e32 v2, v137
	v_mov_b32_e32 v3, v137
	v_mov_b32_e32 v4, 0
	v_mov_b32_e32 v5, v137
	v_mov_b32_e32 v6, v137
	v_mov_b32_e32 v7, v137
	v_mov_b32_e32 v16, 0
	v_mov_b32_e32 v17, v137
	v_mov_b32_e32 v18, v137
	v_mov_b32_e32 v19, v137
	v_mov_b32_e32 v20, 0
	v_mov_b32_e32 v21, v137
	v_mov_b32_e32 v22, v137
	v_mov_b32_e32 v23, v137
	v_mov_b32_e32 v32, 0
	v_mov_b32_e32 v33, v137
	v_mov_b32_e32 v34, v137
	v_mov_b32_e32 v35, v137
	v_mov_b32_e32 v36, 0
	v_mov_b32_e32 v37, v137
	v_mov_b32_e32 v38, v137
	v_mov_b32_e32 v39, v137
	v_mov_b32_e32 v48, 0
	v_mov_b32_e32 v49, v137
	v_mov_b32_e32 v50, v137
	v_mov_b32_e32 v51, v137
	v_mov_b32_e32 v52, 0
	v_mov_b32_e32 v53, v137
	v_mov_b32_e32 v54, v137
	v_mov_b32_e32 v55, v137
	v_mov_b32_e32 v8, 0
	v_mov_b32_e32 v9, v137
	v_mov_b32_e32 v10, v137
	v_mov_b32_e32 v11, v137
	v_mov_b32_e32 v12, 0
	v_mov_b32_e32 v13, v137
	v_mov_b32_e32 v14, v137
	v_mov_b32_e32 v15, v137
	v_mov_b32_e32 v24, 0
	v_mov_b32_e32 v25, v137
	v_mov_b32_e32 v26, v137
	v_mov_b32_e32 v27, v137
	v_mov_b32_e32 v28, 0
	v_mov_b32_e32 v29, v137
	v_mov_b32_e32 v30, v137
	v_mov_b32_e32 v31, v137
	v_mov_b32_e32 v40, 0
	v_mov_b32_e32 v41, v137
	v_mov_b32_e32 v42, v137
	v_mov_b32_e32 v43, v137
	v_mov_b32_e32 v44, 0
	v_mov_b32_e32 v45, v137
	v_mov_b32_e32 v46, v137
	v_mov_b32_e32 v47, v137
	v_mov_b32_e32 v56, 0
	v_mov_b32_e32 v57, v137
	v_mov_b32_e32 v58, v137
	v_mov_b32_e32 v59, v137
	v_mov_b32_e32 v60, 0
	v_mov_b32_e32 v61, v137
	v_mov_b32_e32 v62, v137
	v_mov_b32_e32 v63, v137
	v_mov_b32_e32 v64, 0
	v_mov_b32_e32 v65, v137
	v_mov_b32_e32 v66, v137
	v_mov_b32_e32 v67, v137
	v_mov_b32_e32 v68, 0
	v_mov_b32_e32 v69, v137
	v_mov_b32_e32 v70, v137
	v_mov_b32_e32 v71, v137
	v_mov_b32_e32 v80, 0
	v_mov_b32_e32 v81, v137
	v_mov_b32_e32 v82, v137
	v_mov_b32_e32 v83, v137
	v_mov_b32_e32 v84, 0
	v_mov_b32_e32 v85, v137
	v_mov_b32_e32 v86, v137
	v_mov_b32_e32 v87, v137
	v_mov_b32_e32 v96, 0
	v_mov_b32_e32 v97, v137
	v_mov_b32_e32 v98, v137
	v_mov_b32_e32 v99, v137
	v_mov_b32_e32 v100, 0
	v_mov_b32_e32 v101, v137
	v_mov_b32_e32 v102, v137
	v_mov_b32_e32 v103, v137
	v_mov_b32_e32 v112, 0
	v_mov_b32_e32 v113, v137
	v_mov_b32_e32 v114, v137
	v_mov_b32_e32 v115, v137
	v_mov_b32_e32 v116, 0
	v_mov_b32_e32 v117, v137
	v_mov_b32_e32 v118, v137
	v_mov_b32_e32 v119, v137
	v_mov_b32_e32 v72, 0
	v_mov_b32_e32 v73, v137
	v_mov_b32_e32 v74, v137
	v_mov_b32_e32 v75, v137
	v_mov_b32_e32 v76, 0
	v_mov_b32_e32 v77, v137
	v_mov_b32_e32 v78, v137
	v_mov_b32_e32 v79, v137
	v_mov_b32_e32 v88, 0
	v_mov_b32_e32 v89, v137
	v_mov_b32_e32 v90, v137
	v_mov_b32_e32 v91, v137
	v_mov_b32_e32 v92, 0
	v_mov_b32_e32 v93, v137
	v_mov_b32_e32 v94, v137
	v_mov_b32_e32 v95, v137
	v_mov_b32_e32 v104, 0
	v_mov_b32_e32 v105, v137
	v_mov_b32_e32 v106, v137
	v_mov_b32_e32 v107, v137
	v_mov_b32_e32 v108, 0
	v_mov_b32_e32 v109, v137
	v_mov_b32_e32 v110, v137
	v_mov_b32_e32 v111, v137
	v_mov_b32_e32 v120, 0
	v_mov_b32_e32 v121, v137
	v_mov_b32_e32 v122, v137
	v_mov_b32_e32 v123, v137
	v_mov_b32_e32 v124, 0
	v_mov_b32_e32 v125, v137
	v_mov_b32_e32 v126, v137
	v_mov_b32_e32 v127, v137
	s_lshr_b32 s101, s88, 2
	s_cmp_lg_u32 s101, 0
	s_cbranch_scc1 .Lprio_skip13
	s_setprio 1

.LBB0_2062:
	s_mov_b64 s[22:23], s[12:13]
	s_add_u32 s56, s22, 0x100
	s_addc_u32 s57, s23, 0
	s_add_i32 s54, s55, 1
	s_lshl_b32 s12, s54, 5
	s_add_i32 s12, s12, s30
	s_cmp_lt_i32 s12, 32
	s_cselect_b64 s[20:21], -1, 0
	s_cmp_gt_i32 s12, 31
	s_mov_b32 s16, s53
	s_cselect_b64 s[14:15], -1, 0
	s_ashr_i32 s53, s12, 2
	s_and_b64 s[12:13], s[20:21], exec
	s_cselect_b32 s12, s53, s16
	s_cselect_b32 s16, s34, s34
	s_ashr_i32 s17, s16, 31
	s_lshl_b64 s[16:17], s[16:17], 22
	s_add_u32 s16, s31, s16
	s_addc_u32 s17, s35, s17
	s_and_b64 s[24:25], s[20:21], exec
	s_cselect_b32 s58, s17, s19
	s_cselect_b32 s59, s16, s18
	s_ashr_i32 s13, s12, 31
	s_lshl_b64 s[12:13], s[12:13], 22
	s_add_u32 s12, s36, s12
	s_addc_u32 s13, s37, s13
	s_and_b64 s[24:25], s[20:21], exec
	s_cselect_b32 s60, s13, s23
	s_cselect_b32 s61, s12, s22
	v_lshl_add_u64 v[140:141], s[18:19], 0, v[136:137]
	v_lshl_add_u64 v[142:143], s[18:19], 0, v[138:139]
	s_lshr_b32 s84, s88, 2
	s_mul_i32 s85, s84, 0x3000
	s_add_i32 s85, s85, s1
	s_mul_i32 s96, s84, 0x180000
	s_mov_b32 s97, 0
	s_sub_u32 s86, s96, 0x200000
	s_subb_u32 s87, 0, 0
	s_mov_b32 s62, -2
	s_mov_b64 s[22:23], 0
	s_lshr_b32 s101, s88, 2
	s_cmp_lg_u32 s101, 0
	s_cbranch_scc1 .Lprio_skip14
	s_setprio 1
